# compress unit second matmul h[16x128] @ w2[128x64] on v_mfma_f32_16x16x4_f32 (f32 operands, waves 0-3, one 16-column tile each) instead of the LDS-fed packed-FMA loop
# speedup vs baseline: 1.0122x; 1.0122x over previous
.LBB0_884:
	v_add_u32_e32 v0, 0x400, v162
	s_nop 5
	ds_write2_b32 v0, v52, v53 offset0:2 offset1:131
	v_lshlrev_b32_e32 v0, 2, v147
	v_lshl_or_b32 v0, s44, 13, v0
	v_lshl_add_u64 v[4:5], s[38:39], 0, v[0:1]
	v_add_co_u32_e32 v2, vcc, 0x5c0000, v4
	s_mov_b64 s[40:41], 0x5c0000
	s_nop 0
	v_addc_co_u32_e32 v3, vcc, 0, v5, vcc
	ds_write2_b32 v162, v50, v51 offset1:129
	s_waitcnt lgkmcnt(0)
	s_barrier
	v_lshl_add_u64 v[6:7], v[4:5], 0, s[40:41]
	global_load_dword v0, v[2:3], off
	s_mov_b32 s41, 0x5c1000
	global_load_dword v3, v[6:7], off offset:512
	v_add_co_u32_e32 v4, vcc, s41, v4
	v_mov_b32_e32 v2, 0
	s_nop 0
	v_addc_co_u32_e32 v5, vcc, 0, v5, vcc
	s_mov_b32 s40, 0
	global_load_dword v8, v[6:7], off offset:1024
	global_load_dword v9, v[6:7], off offset:1536
	global_load_dword v10, v[6:7], off offset:2048
	global_load_dword v11, v[6:7], off offset:2560
	global_load_dword v12, v[6:7], off offset:3072
	global_load_dword v13, v[6:7], off offset:3584
	global_load_dword v14, v[4:5], off
	global_load_dword v15, v[4:5], off offset:512
	global_load_dword v16, v[4:5], off offset:1024
	global_load_dword v17, v[4:5], off offset:1536
	global_load_dword v18, v[4:5], off offset:2048
	global_load_dword v19, v[4:5], off offset:2560
	global_load_dword v20, v[4:5], off offset:3072
	global_load_dword v21, v[4:5], off offset:3584
	s_waitcnt vmcnt(15)
	v_add_f32_e32 v0, 0, v0
	s_waitcnt vmcnt(14)
	v_add_f32_e32 v0, v0, v3
	s_waitcnt vmcnt(13)
	v_add_f32_e32 v0, v0, v8
	s_waitcnt vmcnt(12)
	v_add_f32_e32 v0, v0, v9
	s_waitcnt vmcnt(11)
	v_add_f32_e32 v0, v0, v10
	s_waitcnt vmcnt(10)
	v_add_f32_e32 v0, v0, v11
	s_waitcnt vmcnt(9)
	v_add_f32_e32 v0, v0, v12
	s_waitcnt vmcnt(8)
	v_add_f32_e32 v0, v0, v13
	s_waitcnt vmcnt(7)
	v_add_f32_e32 v0, v0, v14
	s_waitcnt vmcnt(6)
	v_add_f32_e32 v0, v0, v15
	s_waitcnt vmcnt(5)
	v_add_f32_e32 v0, v0, v16
	s_waitcnt vmcnt(4)
	v_add_f32_e32 v0, v0, v17
	s_waitcnt vmcnt(3)
	v_add_f32_e32 v0, v0, v18
	s_waitcnt vmcnt(2)
	v_add_f32_e32 v0, v0, v19
	s_waitcnt vmcnt(1)
	v_add_f32_e32 v0, v0, v20
	s_waitcnt vmcnt(0)
	v_add_f32_e32 v0, v0, v21
	ds_read_b32 v3, v163
	s_waitcnt lgkmcnt(0)
	v_add_f32_e32 v3, v0, v3
	v_mul_f32_e32 v4, 0xbfb8aa3b, v3
	v_exp_f32_e32 v4, v4
	s_nop 0
	v_add_f32_e32 v4, 1.0, v4
	v_rcp_f32_e32 v4, v4
	s_nop 0
	v_mul_f32_e32 v3, v3, v4
	ds_write_b32 v163, v3
	ds_read_b32 v3, v163 offset:2064
	s_waitcnt lgkmcnt(0)
	v_add_f32_e32 v3, v0, v3
	v_mul_f32_e32 v4, 0xbfb8aa3b, v3
	v_exp_f32_e32 v4, v4
	s_nop 0
	v_add_f32_e32 v4, 1.0, v4
	v_rcp_f32_e32 v4, v4
	s_nop 0
	v_mul_f32_e32 v3, v3, v4
	ds_write_b32 v163, v3 offset:2064
	ds_read_b32 v3, v163 offset:4128
	s_waitcnt lgkmcnt(0)
	v_add_f32_e32 v3, v0, v3
	v_mul_f32_e32 v4, 0xbfb8aa3b, v3
	v_exp_f32_e32 v4, v4
	s_nop 0
	v_add_f32_e32 v4, 1.0, v4
	v_rcp_f32_e32 v4, v4
	s_nop 0
	v_mul_f32_e32 v3, v3, v4
	ds_write_b32 v163, v3 offset:4128
	ds_read_b32 v3, v163 offset:6192
	s_waitcnt lgkmcnt(0)
	v_add_f32_e32 v0, v0, v3
	v_mul_f32_e32 v3, 0xbfb8aa3b, v0
	v_exp_f32_e32 v3, v3
	s_nop 0
	v_add_f32_e32 v3, 1.0, v3
	v_rcp_f32_e32 v3, v3
	s_nop 0
	v_mul_f32_e32 v0, v0, v3
	ds_write_b32 v163, v0 offset:6192
	s_waitcnt lgkmcnt(0)
	s_barrier
	v_readlane_b32 s32, v254, 3
	s_cmp_gt_u32 s32, 3
	s_cbranch_scc1 .Lc2m_skip_0
	v_and_b32_e32 v8, 15, v202
	v_lshrrev_b32_e32 v9, 4, v202
	v_mul_u32_u24_e32 v10, 0x204, v8
	v_lshl_add_u32 v10, v9, 2, v10
	v_lshlrev_b32_e32 v11, 8, v9
	v_lshl_add_u32 v11, v8, 2, v11
	s_lshl_b32 s32, s32, 6
	v_add_u32_e32 v11, s32, v11
	v_mov_b32_e32 v44, 0
	v_mov_b32_e32 v45, 0
	v_mov_b32_e32 v46, 0
	v_mov_b32_e32 v47, 0
	ds_read_b32 v12, v10 offset:0
	ds_read_b32 v13, v11 offset:12416
	ds_read_b32 v14, v10 offset:16
	ds_read_b32 v15, v11 offset:13440
	ds_read_b32 v16, v10 offset:32
	ds_read_b32 v17, v11 offset:14464
	ds_read_b32 v18, v10 offset:48
	ds_read_b32 v19, v11 offset:15488
	ds_read_b32 v20, v10 offset:64
	ds_read_b32 v21, v11 offset:16512
	ds_read_b32 v22, v10 offset:80
	ds_read_b32 v23, v11 offset:17536
	ds_read_b32 v24, v10 offset:96
	ds_read_b32 v25, v11 offset:18560
	ds_read_b32 v26, v10 offset:112
	ds_read_b32 v27, v11 offset:19584
	s_waitcnt lgkmcnt(14)
	v_mfma_f32_16x16x4_f32 v[44:47], v12, v13, v[44:47]
	ds_read_b32 v12, v10 offset:128
	ds_read_b32 v13, v11 offset:20608
	s_waitcnt lgkmcnt(14)
	v_mfma_f32_16x16x4_f32 v[44:47], v14, v15, v[44:47]
	ds_read_b32 v14, v10 offset:144
	ds_read_b32 v15, v11 offset:21632
	s_waitcnt lgkmcnt(14)
	v_mfma_f32_16x16x4_f32 v[44:47], v16, v17, v[44:47]
	ds_read_b32 v16, v10 offset:160
	ds_read_b32 v17, v11 offset:22656
	s_waitcnt lgkmcnt(14)
	v_mfma_f32_16x16x4_f32 v[44:47], v18, v19, v[44:47]
	ds_read_b32 v18, v10 offset:176
	ds_read_b32 v19, v11 offset:23680
	s_waitcnt lgkmcnt(14)
	v_mfma_f32_16x16x4_f32 v[44:47], v20, v21, v[44:47]
	ds_read_b32 v20, v10 offset:192
	ds_read_b32 v21, v11 offset:24704
	s_waitcnt lgkmcnt(14)
	v_mfma_f32_16x16x4_f32 v[44:47], v22, v23, v[44:47]
	ds_read_b32 v22, v10 offset:208
	ds_read_b32 v23, v11 offset:25728
	s_waitcnt lgkmcnt(14)
	v_mfma_f32_16x16x4_f32 v[44:47], v24, v25, v[44:47]
	ds_read_b32 v24, v10 offset:224
	ds_read_b32 v25, v11 offset:26752
	s_waitcnt lgkmcnt(14)
	v_mfma_f32_16x16x4_f32 v[44:47], v26, v27, v[44:47]
	ds_read_b32 v26, v10 offset:240
	ds_read_b32 v27, v11 offset:27776
	s_waitcnt lgkmcnt(14)
	v_mfma_f32_16x16x4_f32 v[44:47], v12, v13, v[44:47]
	ds_read_b32 v12, v10 offset:256
	ds_read_b32 v13, v11 offset:28800
	s_waitcnt lgkmcnt(14)
	v_mfma_f32_16x16x4_f32 v[44:47], v14, v15, v[44:47]
	ds_read_b32 v14, v10 offset:272
	ds_read_b32 v15, v11 offset:29824
	s_waitcnt lgkmcnt(14)
	v_mfma_f32_16x16x4_f32 v[44:47], v16, v17, v[44:47]
	ds_read_b32 v16, v10 offset:288
	ds_read_b32 v17, v11 offset:30848
	s_waitcnt lgkmcnt(14)
	v_mfma_f32_16x16x4_f32 v[44:47], v18, v19, v[44:47]
	ds_read_b32 v18, v10 offset:304
	ds_read_b32 v19, v11 offset:31872
	s_waitcnt lgkmcnt(14)
	v_mfma_f32_16x16x4_f32 v[44:47], v20, v21, v[44:47]
	ds_read_b32 v20, v10 offset:320
	ds_read_b32 v21, v11 offset:32896
	s_waitcnt lgkmcnt(14)
	v_mfma_f32_16x16x4_f32 v[44:47], v22, v23, v[44:47]
	ds_read_b32 v22, v10 offset:336
	ds_read_b32 v23, v11 offset:33920
	s_waitcnt lgkmcnt(14)
	v_mfma_f32_16x16x4_f32 v[44:47], v24, v25, v[44:47]
	ds_read_b32 v24, v10 offset:352
	ds_read_b32 v25, v11 offset:34944
	s_waitcnt lgkmcnt(14)
	v_mfma_f32_16x16x4_f32 v[44:47], v26, v27, v[44:47]
	ds_read_b32 v26, v10 offset:368
	ds_read_b32 v27, v11 offset:35968
	s_waitcnt lgkmcnt(14)
	v_mfma_f32_16x16x4_f32 v[44:47], v12, v13, v[44:47]
	ds_read_b32 v12, v10 offset:384
	ds_read_b32 v13, v11 offset:36992
	s_waitcnt lgkmcnt(14)
	v_mfma_f32_16x16x4_f32 v[44:47], v14, v15, v[44:47]
	ds_read_b32 v14, v10 offset:400
	ds_read_b32 v15, v11 offset:38016
	s_waitcnt lgkmcnt(14)
	v_mfma_f32_16x16x4_f32 v[44:47], v16, v17, v[44:47]
	ds_read_b32 v16, v10 offset:416
	ds_read_b32 v17, v11 offset:39040
	s_waitcnt lgkmcnt(14)
	v_mfma_f32_16x16x4_f32 v[44:47], v18, v19, v[44:47]
	ds_read_b32 v18, v10 offset:432
	ds_read_b32 v19, v11 offset:40064
	s_waitcnt lgkmcnt(14)
	v_mfma_f32_16x16x4_f32 v[44:47], v20, v21, v[44:47]
	ds_read_b32 v20, v10 offset:448
	ds_read_b32 v21, v11 offset:41088
	s_waitcnt lgkmcnt(14)
	v_mfma_f32_16x16x4_f32 v[44:47], v22, v23, v[44:47]
	ds_read_b32 v22, v10 offset:464
	ds_read_b32 v23, v11 offset:42112
	s_waitcnt lgkmcnt(14)
	v_mfma_f32_16x16x4_f32 v[44:47], v24, v25, v[44:47]
	ds_read_b32 v24, v10 offset:480
	ds_read_b32 v25, v11 offset:43136
	s_waitcnt lgkmcnt(14)
	v_mfma_f32_16x16x4_f32 v[44:47], v26, v27, v[44:47]
	ds_read_b32 v26, v10 offset:496
	ds_read_b32 v27, v11 offset:44160
	s_waitcnt lgkmcnt(14)
	v_mfma_f32_16x16x4_f32 v[44:47], v12, v13, v[44:47]
	s_waitcnt lgkmcnt(12)
	v_mfma_f32_16x16x4_f32 v[44:47], v14, v15, v[44:47]
	s_waitcnt lgkmcnt(10)
	v_mfma_f32_16x16x4_f32 v[44:47], v16, v17, v[44:47]
	s_waitcnt lgkmcnt(8)
	v_mfma_f32_16x16x4_f32 v[44:47], v18, v19, v[44:47]
	s_waitcnt lgkmcnt(6)
	v_mfma_f32_16x16x4_f32 v[44:47], v20, v21, v[44:47]
	s_waitcnt lgkmcnt(4)
	v_mfma_f32_16x16x4_f32 v[44:47], v22, v23, v[44:47]
	s_waitcnt lgkmcnt(2)
	v_mfma_f32_16x16x4_f32 v[44:47], v24, v25, v[44:47]
	s_waitcnt lgkmcnt(0)
	v_mfma_f32_16x16x4_f32 v[44:47], v26, v27, v[44:47]
	v_lshlrev_b32_e32 v9, 2, v9
	v_mul_u32_u24_e32 v9, 0x104, v9
	v_lshl_add_u32 v9, v8, 2, v9
	v_add_u32_e32 v9, s32, v9
	s_nop 7
	ds_write_b32 v9, v44 offset:8256
	ds_write_b32 v9, v45 offset:8516
	ds_write_b32 v9, v46 offset:8776
	ds_write_b32 v9, v47 offset:9036
.Lc2m_skip_0:
	s_waitcnt lgkmcnt(0)
	s_barrier
	v_add_u32_e32 v4, 0x2040, v150
	ds_read2_b32 v[2:3], v4 offset1:1
	s_waitcnt lgkmcnt(0)
	v_add_u32_e32 v0, s45, v148
	s_cmp_eq_u32 s44, 0
	s_mov_b64 s[40:41], 0x880000
	s_cbranch_scc0 .LBB0_823
	v_add_u32_e32 v4, 0x2040, v150
	ds_write2_b32 v4, v2, v3 offset1:1
	v_lshl_add_u32 v4, v0, 9, v151
	v_ashrrev_i32_e32 v5, 31, v4
	v_lshl_add_u64 v[4:5], v[4:5], 2, s[38:39]
	v_add_co_u32_e32 v6, vcc, 0x500000, v4
	s_waitcnt lgkmcnt(0)
	s_nop 0
	v_addc_co_u32_e32 v7, vcc, 0, v5, vcc
	v_add_co_u32_e32 v4, vcc, 0x540000, v4
	s_barrier
	s_nop 0
	v_addc_co_u32_e32 v5, vcc, 0, v5, vcc
	global_load_dwordx2 v[6:7], v[6:7], off
	ds_read2_b32 v[8:9], v164 offset1:1
	global_load_dwordx2 v[4:5], v[4:5], off
	v_readlane_b32 s40, v255, 27
	v_readlane_b32 s41, v255, 28
	s_waitcnt vmcnt(0) lgkmcnt(0)
	v_pk_mul_f32 v[4:5], v[4:5], v[8:9]
	s_nop 0
	v_cndmask_b32_e64 v5, v5, -v5, s[40:41]
	v_cndmask_b32_e64 v4, v4, -v4, s[40:41]
	v_pk_fma_f32 v[2:3], v[2:3], v[6:7], v[4:5]
	s_mov_b64 s[40:41], 0x800000
	s_branch .LBB0_823

.LBB0_2071:
	v_add_u32_e32 v0, 0x400, v163
	s_nop 5
	ds_write2_b32 v0, v52, v53 offset0:2 offset1:131
	v_lshlrev_b32_e32 v0, 2, v147
	v_lshl_or_b32 v0, s46, 13, v0
	v_lshl_add_u64 v[4:5], s[38:39], 0, v[0:1]
	v_add_co_u32_e32 v2, vcc, 0x5c0000, v4
	s_mov_b64 s[40:41], 0x5c0000
	s_nop 0
	v_addc_co_u32_e32 v3, vcc, 0, v5, vcc
	ds_write2_b32 v163, v50, v51 offset1:129
	s_waitcnt lgkmcnt(0)
	s_barrier
	v_lshl_add_u64 v[6:7], v[4:5], 0, s[40:41]
	global_load_dword v0, v[2:3], off
	s_mov_b32 s41, 0x5c1000
	global_load_dword v3, v[6:7], off offset:512
	v_add_co_u32_e32 v4, vcc, s41, v4
	v_mov_b32_e32 v2, 0
	s_nop 0
	v_addc_co_u32_e32 v5, vcc, 0, v5, vcc
	s_mov_b32 s40, 0
	global_load_dword v8, v[6:7], off offset:1024
	global_load_dword v9, v[6:7], off offset:1536
	global_load_dword v10, v[6:7], off offset:2048
	global_load_dword v11, v[6:7], off offset:2560
	global_load_dword v12, v[6:7], off offset:3072
	global_load_dword v13, v[6:7], off offset:3584
	global_load_dword v14, v[4:5], off
	global_load_dword v15, v[4:5], off offset:512
	global_load_dword v16, v[4:5], off offset:1024
	global_load_dword v17, v[4:5], off offset:1536
	global_load_dword v18, v[4:5], off offset:2048
	global_load_dword v19, v[4:5], off offset:2560
	global_load_dword v20, v[4:5], off offset:3072
	global_load_dword v21, v[4:5], off offset:3584
	s_waitcnt vmcnt(15)
	v_add_f32_e32 v0, 0, v0
	s_waitcnt vmcnt(14)
	v_add_f32_e32 v0, v0, v3
	s_waitcnt vmcnt(13)
	v_add_f32_e32 v0, v0, v8
	s_waitcnt vmcnt(12)
	v_add_f32_e32 v0, v0, v9
	s_waitcnt vmcnt(11)
	v_add_f32_e32 v0, v0, v10
	s_waitcnt vmcnt(10)
	v_add_f32_e32 v0, v0, v11
	s_waitcnt vmcnt(9)
	v_add_f32_e32 v0, v0, v12
	s_waitcnt vmcnt(8)
	v_add_f32_e32 v0, v0, v13
	s_waitcnt vmcnt(7)
	v_add_f32_e32 v0, v0, v14
	s_waitcnt vmcnt(6)
	v_add_f32_e32 v0, v0, v15
	s_waitcnt vmcnt(5)
	v_add_f32_e32 v0, v0, v16
	s_waitcnt vmcnt(4)
	v_add_f32_e32 v0, v0, v17
	s_waitcnt vmcnt(3)
	v_add_f32_e32 v0, v0, v18
	s_waitcnt vmcnt(2)
	v_add_f32_e32 v0, v0, v19
	s_waitcnt vmcnt(1)
	v_add_f32_e32 v0, v0, v20
	s_waitcnt vmcnt(0)
	v_add_f32_e32 v0, v0, v21
	ds_read_b32 v3, v164
	s_waitcnt lgkmcnt(0)
	v_add_f32_e32 v3, v0, v3
	v_mul_f32_e32 v4, 0xbfb8aa3b, v3
	v_exp_f32_e32 v4, v4
	s_nop 0
	v_add_f32_e32 v4, 1.0, v4
	v_rcp_f32_e32 v4, v4
	s_nop 0
	v_mul_f32_e32 v3, v3, v4
	ds_write_b32 v164, v3
	ds_read_b32 v3, v164 offset:2064
	s_waitcnt lgkmcnt(0)
	v_add_f32_e32 v3, v0, v3
	v_mul_f32_e32 v4, 0xbfb8aa3b, v3
	v_exp_f32_e32 v4, v4
	s_nop 0
	v_add_f32_e32 v4, 1.0, v4
	v_rcp_f32_e32 v4, v4
	s_nop 0
	v_mul_f32_e32 v3, v3, v4
	ds_write_b32 v164, v3 offset:2064
	ds_read_b32 v3, v164 offset:4128
	s_waitcnt lgkmcnt(0)
	v_add_f32_e32 v3, v0, v3
	v_mul_f32_e32 v4, 0xbfb8aa3b, v3
	v_exp_f32_e32 v4, v4
	s_nop 0
	v_add_f32_e32 v4, 1.0, v4
	v_rcp_f32_e32 v4, v4
	s_nop 0
	v_mul_f32_e32 v3, v3, v4
	ds_write_b32 v164, v3 offset:4128
	ds_read_b32 v3, v164 offset:6192
	s_waitcnt lgkmcnt(0)
	v_add_f32_e32 v0, v0, v3
	v_mul_f32_e32 v3, 0xbfb8aa3b, v0
	v_exp_f32_e32 v3, v3
	s_nop 0
	v_add_f32_e32 v3, 1.0, v3
	v_rcp_f32_e32 v3, v3
	s_nop 0
	v_mul_f32_e32 v0, v0, v3
	ds_write_b32 v164, v0 offset:6192
	s_waitcnt lgkmcnt(0)
	s_barrier
	v_readlane_b32 s32, v254, 3
	s_cmp_gt_u32 s32, 3
	s_cbranch_scc1 .Lc2m_skip_1
	v_and_b32_e32 v8, 15, v202
	v_lshrrev_b32_e32 v9, 4, v202
	v_mul_u32_u24_e32 v10, 0x204, v8
	v_lshl_add_u32 v10, v9, 2, v10
	v_lshlrev_b32_e32 v11, 8, v9
	v_lshl_add_u32 v11, v8, 2, v11
	s_lshl_b32 s32, s32, 6
	v_add_u32_e32 v11, s32, v11
	v_mov_b32_e32 v44, 0
	v_mov_b32_e32 v45, 0
	v_mov_b32_e32 v46, 0
	v_mov_b32_e32 v47, 0
	ds_read_b32 v12, v10 offset:0
	ds_read_b32 v13, v11 offset:12416
	ds_read_b32 v14, v10 offset:16
	ds_read_b32 v15, v11 offset:13440
	ds_read_b32 v16, v10 offset:32
	ds_read_b32 v17, v11 offset:14464
	ds_read_b32 v18, v10 offset:48
	ds_read_b32 v19, v11 offset:15488
	ds_read_b32 v20, v10 offset:64
	ds_read_b32 v21, v11 offset:16512
	ds_read_b32 v22, v10 offset:80
	ds_read_b32 v23, v11 offset:17536
	ds_read_b32 v24, v10 offset:96
	ds_read_b32 v25, v11 offset:18560
	ds_read_b32 v26, v10 offset:112
	ds_read_b32 v27, v11 offset:19584
	s_waitcnt lgkmcnt(14)
	v_mfma_f32_16x16x4_f32 v[44:47], v12, v13, v[44:47]
	ds_read_b32 v12, v10 offset:128
	ds_read_b32 v13, v11 offset:20608
	s_waitcnt lgkmcnt(14)
	v_mfma_f32_16x16x4_f32 v[44:47], v14, v15, v[44:47]
	ds_read_b32 v14, v10 offset:144
	ds_read_b32 v15, v11 offset:21632
	s_waitcnt lgkmcnt(14)
	v_mfma_f32_16x16x4_f32 v[44:47], v16, v17, v[44:47]
	ds_read_b32 v16, v10 offset:160
	ds_read_b32 v17, v11 offset:22656
	s_waitcnt lgkmcnt(14)
	v_mfma_f32_16x16x4_f32 v[44:47], v18, v19, v[44:47]
	ds_read_b32 v18, v10 offset:176
	ds_read_b32 v19, v11 offset:23680
	s_waitcnt lgkmcnt(14)
	v_mfma_f32_16x16x4_f32 v[44:47], v20, v21, v[44:47]
	ds_read_b32 v20, v10 offset:192
	ds_read_b32 v21, v11 offset:24704
	s_waitcnt lgkmcnt(14)
	v_mfma_f32_16x16x4_f32 v[44:47], v22, v23, v[44:47]
	ds_read_b32 v22, v10 offset:208
	ds_read_b32 v23, v11 offset:25728
	s_waitcnt lgkmcnt(14)
	v_mfma_f32_16x16x4_f32 v[44:47], v24, v25, v[44:47]
	ds_read_b32 v24, v10 offset:224
	ds_read_b32 v25, v11 offset:26752
	s_waitcnt lgkmcnt(14)
	v_mfma_f32_16x16x4_f32 v[44:47], v26, v27, v[44:47]
	ds_read_b32 v26, v10 offset:240
	ds_read_b32 v27, v11 offset:27776
	s_waitcnt lgkmcnt(14)
	v_mfma_f32_16x16x4_f32 v[44:47], v12, v13, v[44:47]
	ds_read_b32 v12, v10 offset:256
	ds_read_b32 v13, v11 offset:28800
	s_waitcnt lgkmcnt(14)
	v_mfma_f32_16x16x4_f32 v[44:47], v14, v15, v[44:47]
	ds_read_b32 v14, v10 offset:272
	ds_read_b32 v15, v11 offset:29824
	s_waitcnt lgkmcnt(14)
	v_mfma_f32_16x16x4_f32 v[44:47], v16, v17, v[44:47]
	ds_read_b32 v16, v10 offset:288
	ds_read_b32 v17, v11 offset:30848
	s_waitcnt lgkmcnt(14)
	v_mfma_f32_16x16x4_f32 v[44:47], v18, v19, v[44:47]
	ds_read_b32 v18, v10 offset:304
	ds_read_b32 v19, v11 offset:31872
	s_waitcnt lgkmcnt(14)
	v_mfma_f32_16x16x4_f32 v[44:47], v20, v21, v[44:47]
	ds_read_b32 v20, v10 offset:320
	ds_read_b32 v21, v11 offset:32896
	s_waitcnt lgkmcnt(14)
	v_mfma_f32_16x16x4_f32 v[44:47], v22, v23, v[44:47]
	ds_read_b32 v22, v10 offset:336
	ds_read_b32 v23, v11 offset:33920
	s_waitcnt lgkmcnt(14)
	v_mfma_f32_16x16x4_f32 v[44:47], v24, v25, v[44:47]
	ds_read_b32 v24, v10 offset:352
	ds_read_b32 v25, v11 offset:34944
	s_waitcnt lgkmcnt(14)
	v_mfma_f32_16x16x4_f32 v[44:47], v26, v27, v[44:47]
	ds_read_b32 v26, v10 offset:368
	ds_read_b32 v27, v11 offset:35968
	s_waitcnt lgkmcnt(14)
	v_mfma_f32_16x16x4_f32 v[44:47], v12, v13, v[44:47]
	ds_read_b32 v12, v10 offset:384
	ds_read_b32 v13, v11 offset:36992
	s_waitcnt lgkmcnt(14)
	v_mfma_f32_16x16x4_f32 v[44:47], v14, v15, v[44:47]
	ds_read_b32 v14, v10 offset:400
	ds_read_b32 v15, v11 offset:38016
	s_waitcnt lgkmcnt(14)
	v_mfma_f32_16x16x4_f32 v[44:47], v16, v17, v[44:47]
	ds_read_b32 v16, v10 offset:416
	ds_read_b32 v17, v11 offset:39040
	s_waitcnt lgkmcnt(14)
	v_mfma_f32_16x16x4_f32 v[44:47], v18, v19, v[44:47]
	ds_read_b32 v18, v10 offset:432
	ds_read_b32 v19, v11 offset:40064
	s_waitcnt lgkmcnt(14)
	v_mfma_f32_16x16x4_f32 v[44:47], v20, v21, v[44:47]
	ds_read_b32 v20, v10 offset:448
	ds_read_b32 v21, v11 offset:41088
	s_waitcnt lgkmcnt(14)
	v_mfma_f32_16x16x4_f32 v[44:47], v22, v23, v[44:47]
	ds_read_b32 v22, v10 offset:464
	ds_read_b32 v23, v11 offset:42112
	s_waitcnt lgkmcnt(14)
	v_mfma_f32_16x16x4_f32 v[44:47], v24, v25, v[44:47]
	ds_read_b32 v24, v10 offset:480
	ds_read_b32 v25, v11 offset:43136
	s_waitcnt lgkmcnt(14)
	v_mfma_f32_16x16x4_f32 v[44:47], v26, v27, v[44:47]
	ds_read_b32 v26, v10 offset:496
	ds_read_b32 v27, v11 offset:44160
	s_waitcnt lgkmcnt(14)
	v_mfma_f32_16x16x4_f32 v[44:47], v12, v13, v[44:47]
	s_waitcnt lgkmcnt(12)
	v_mfma_f32_16x16x4_f32 v[44:47], v14, v15, v[44:47]
	s_waitcnt lgkmcnt(10)
	v_mfma_f32_16x16x4_f32 v[44:47], v16, v17, v[44:47]
	s_waitcnt lgkmcnt(8)
	v_mfma_f32_16x16x4_f32 v[44:47], v18, v19, v[44:47]
	s_waitcnt lgkmcnt(6)
	v_mfma_f32_16x16x4_f32 v[44:47], v20, v21, v[44:47]
	s_waitcnt lgkmcnt(4)
	v_mfma_f32_16x16x4_f32 v[44:47], v22, v23, v[44:47]
	s_waitcnt lgkmcnt(2)
	v_mfma_f32_16x16x4_f32 v[44:47], v24, v25, v[44:47]
	s_waitcnt lgkmcnt(0)
	v_mfma_f32_16x16x4_f32 v[44:47], v26, v27, v[44:47]
	v_lshlrev_b32_e32 v9, 2, v9
	v_mul_u32_u24_e32 v9, 0x104, v9
	v_lshl_add_u32 v9, v8, 2, v9
	v_add_u32_e32 v9, s32, v9
	s_nop 7
	ds_write_b32 v9, v44 offset:8256
	ds_write_b32 v9, v45 offset:8516
	ds_write_b32 v9, v46 offset:8776
	ds_write_b32 v9, v47 offset:9036
.Lc2m_skip_1:
	s_waitcnt lgkmcnt(0)
	s_barrier
	v_add_u32_e32 v4, 0x2040, v150
	ds_read2_b32 v[2:3], v4 offset1:1
	s_waitcnt lgkmcnt(0)
	v_add_u32_e32 v0, s45, v148
	s_cmp_eq_u32 s44, 0
	s_mov_b64 s[40:41], 0x880000
	s_cbranch_scc0 .LBB0_2010
	v_add_u32_e32 v4, 0x2040, v150
	ds_write2_b32 v4, v2, v3 offset1:1
	v_lshl_add_u32 v4, v0, 9, v151
	v_ashrrev_i32_e32 v5, 31, v4
	v_lshl_add_u64 v[4:5], v[4:5], 2, s[38:39]
	v_add_co_u32_e32 v6, vcc, 0x500000, v4
	s_waitcnt lgkmcnt(0)
	s_nop 0
	v_addc_co_u32_e32 v7, vcc, 0, v5, vcc
	v_add_co_u32_e32 v4, vcc, 0x540000, v4
	s_barrier
	s_nop 0
	v_addc_co_u32_e32 v5, vcc, 0, v5, vcc
	global_load_dwordx2 v[6:7], v[6:7], off
	ds_read2_b32 v[8:9], v165 offset1:1
	global_load_dwordx2 v[4:5], v[4:5], off
	v_readlane_b32 s40, v255, 34
	v_readlane_b32 s41, v255, 35
	s_waitcnt vmcnt(0) lgkmcnt(0)
	v_pk_mul_f32 v[4:5], v[4:5], v[8:9]
	s_nop 0
	v_cndmask_b32_e64 v5, v5, -v5, s[40:41]
	v_cndmask_b32_e64 v4, v4, -v4, s[40:41]
	v_pk_fma_f32 v[2:3], v[2:3], v[6:7], v[4:5]
	s_mov_b64 s[40:41], 0x800000
	s_branch .LBB0_2010
